# proj and gate-up: row-statistic loads of the once-per-phase scale computation issued in the phase prologue into the cached-scale register pairs
# baseline (speedup 1.0000x reference)
.LBB0_336:
	s_sext_i32_i16 s30, s20
	s_add_u32 s20, s24, 0x2d300000
	s_addc_u32 s21, s25, 0
	v_bfe_u32 v21, v18, 4, 2
	s_lshl_b32 s16, s16, 5
	v_and_b32_e32 v19, 15, v18
	v_lshlrev_b32_e32 v20, 3, v21
	v_lshlrev_b32_e32 v21, 4, v21
	v_lshlrev_b32_e32 v18, 2, v18
	s_and_b32 s19, s16, 0x60
	v_lshl_or_b32 v145, s17, 6, v19
	v_lshl_or_b32 v19, v19, 6, v21
	s_lshl_b32 s17, s17, 13
	v_and_b32_e32 v18, 32, v18
	s_lshl_b32 s16, s19, 7
	s_add_i32 m0, s12, 0x18000
	v_lshl_add_u64 v[10:11], v[10:11], 0, s[68:69]
	v_bitop3_b32 v22, v19, s17, v18 bitop3:0xde
	v_bitop3_b32 v149, v19, s16, v18 bitop3:0xde
	s_nop 0
	global_load_lds_dwordx4 v[10:11], off
	v_lshl_add_u64 v[8:9], v[8:9], 0, s[68:69]
	s_add_i32 m0, s12, 0x1a000
	s_add_i32 s16, s12, 0x8000
	s_add_i32 s17, s12, 0xa000
	global_load_lds_dwordx4 v[8:9], off
	v_lshl_add_u64 v[4:5], v[4:5], 0, s[68:69]
	s_mov_b32 m0, s16
	s_add_u32 s22, s44, 0x80080
	global_load_lds_dwordx4 v[4:5], off
	v_lshl_add_u64 v[4:5], v[6:7], 0, s[68:69]
	s_mov_b32 m0, s17
	s_addc_u32 s23, s45, 0
	global_load_lds_dwordx4 v[4:5], off
	s_add_i32 m0, s12, 0x1c000
	v_lshl_add_u64 v[4:5], s[22:23], 0, v[2:3]
	global_load_lds_dwordx4 v[4:5], off
	v_lshl_add_u64 v[4:5], s[22:23], 0, v[0:1]
	s_add_i32 m0, s12, 0x1e000
	v_cmp_lt_i32_e32 vcc, v236, v237
	global_load_lds_dwordx4 v[4:5], off
	s_nop 0
	v_cndmask_b32_e32 v4, v234, v236, vcc
	v_cmp_lt_i32_e32 vcc, v252, v237
	v_lshlrev_b32_e32 v153, 2, v4
	v_mov_b32_e32 v21, v3
	v_cndmask_b32_e32 v4, v234, v252, vcc
	v_lshlrev_b32_e32 v159, 2, v4
	v_lshl_add_u64 v[4:5], s[24:25], 0, v[20:21]
	s_mov_b64 s[24:25], 0x800000
	v_lshl_add_u64 v[136:137], v[4:5], 0, s[24:25]
	v_lshl_add_u32 v168, s42, 8, v145
	v_or_b32_e32 v186, 16, v168
	v_or_b32_e32 v187, 32, v168
	v_or_b32_e32 v188, 48, v168
	v_add_u32_e32 v189, 0x80, v168
	v_add_u32_e32 v190, 0x90, v168
	v_add_u32_e32 v191, 0xa0, v168
	v_add_u32_e32 v192, 0xb0, v168
	v_mad_u64_u32 v[170:171], s[100:101], v168, 32, v[136:137]
	v_mad_u64_u32 v[172:173], s[100:101], v186, 32, v[136:137]
	v_mad_u64_u32 v[174:175], s[100:101], v187, 32, v[136:137]
	v_mad_u64_u32 v[176:177], s[100:101], v188, 32, v[136:137]
	v_mad_u64_u32 v[178:179], s[100:101], v189, 32, v[136:137]
	v_mad_u64_u32 v[180:181], s[100:101], v190, 32, v[136:137]
	v_mad_u64_u32 v[182:183], s[100:101], v191, 32, v[136:137]
	v_mad_u64_u32 v[184:185], s[100:101], v192, 32, v[136:137]
	global_load_dwordx2 v[228:229], v[170:171], off
	global_load_dwordx2 v[230:231], v[172:173], off
	global_load_dwordx2 v[238:239], v[174:175], off
	global_load_dwordx2 v[242:243], v[176:177], off
	global_load_dwordx2 v[244:245], v[178:179], off
	global_load_dwordx2 v[246:247], v[180:181], off
	global_load_dwordx2 v[248:249], v[182:183], off
	global_load_dwordx2 v[250:251], v[184:185], off
	v_lshlrev_b32_e32 v4, 15, v12
	v_and_b32_e32 v4, 0xffff0000, v4
	v_lshl_add_u32 v4, v13, 12, v4
	v_and_b32_e32 v5, 1, v12
	v_lshl_or_b32 v4, v5, 6, v4
	v_lshl_add_u32 v138, v14, 1, v4
	v_lshlrev_b32_e32 v4, 15, v16
	v_and_b32_e32 v4, 0xffff0000, v4
	s_waitcnt vmcnt(16)
	s_barrier
	s_waitcnt vmcnt(14)
	v_lshl_add_u32 v4, v15, 12, v4
	v_and_b32_e32 v5, 1, v16
	s_cmpk_lt_u32 s18, 0x100
	v_lshl_or_b32 v4, v5, 6, v4
	s_cselect_b64 s[22:23], -1, 0
	s_ashr_i32 s18, s4, 31
	v_or_b32_e32 v163, s19, v20
	v_mov_b32_e32 v139, v3
	v_lshl_add_u32 v140, v17, 1, v4
	v_mov_b32_e32 v141, v3
	s_mov_b32 s19, 0
	v_add_u32_e32 v167, 0, v22
	s_barrier
	s_branch .LBB0_339

.LBB0_345:
	v_lshl_add_u32 v168, s42, 8, v145
	v_or_b32_e32 v164, 16, v168
	v_or_b32_e32 v160, 32, v168
	v_or_b32_e32 v156, 48, v168
	v_add_u32_e32 v154, 0x80, v168
	v_add_u32_e32 v150, 0x90, v168
	v_add_u32_e32 v146, 0xa0, v168
	v_add_u32_e32 v142, 0xb0, v168
	s_cmp_eq_u32 s42, s98
	s_cbranch_scc1 .Lpj_scales_ready
	s_mov_b32 s98, s42
	s_waitcnt vmcnt(0)
	v_add_f32_e32 v228, v228, v229
	v_add_f32_e32 v230, v230, v231
	v_add_f32_e32 v238, v238, v239
	v_add_f32_e32 v242, v242, v243
	v_add_f32_e32 v244, v244, v245
	v_add_f32_e32 v246, v246, v247
	v_add_f32_e32 v248, v248, v249
	v_add_f32_e32 v250, v250, v251
	ds_bpermute_b32 v229, v153, v228
	ds_bpermute_b32 v231, v153, v230
	ds_bpermute_b32 v239, v153, v238
	ds_bpermute_b32 v243, v153, v242
	ds_bpermute_b32 v245, v153, v244
	ds_bpermute_b32 v247, v153, v246
	ds_bpermute_b32 v249, v153, v248
	ds_bpermute_b32 v251, v153, v250
	s_waitcnt lgkmcnt(0)
	v_add_f32_e32 v228, v228, v229
	v_add_f32_e32 v230, v230, v231
	v_add_f32_e32 v238, v238, v239
	v_add_f32_e32 v242, v242, v243
	v_add_f32_e32 v244, v244, v245
	v_add_f32_e32 v246, v246, v247
	v_add_f32_e32 v248, v248, v249
	v_add_f32_e32 v250, v250, v251
	ds_bpermute_b32 v229, v159, v228
	ds_bpermute_b32 v231, v159, v230
	ds_bpermute_b32 v239, v159, v238
	ds_bpermute_b32 v243, v159, v242
	ds_bpermute_b32 v245, v159, v244
	ds_bpermute_b32 v247, v159, v246
	ds_bpermute_b32 v249, v159, v248
	ds_bpermute_b32 v251, v159, v250
	s_waitcnt lgkmcnt(0)
	v_add_f32_e32 v228, v228, v229
	v_add_f32_e32 v230, v230, v231
	v_add_f32_e32 v238, v238, v239
	v_add_f32_e32 v242, v242, v243
	v_add_f32_e32 v244, v244, v245
	v_add_f32_e32 v246, v246, v247
	v_add_f32_e32 v248, v248, v249
	v_add_f32_e32 v250, v250, v251
	v_fmamk_f32 v228, v228, 0x3a000000, v232
	v_fmamk_f32 v230, v230, 0x3a000000, v232
	v_fmamk_f32 v238, v238, 0x3a000000, v232
	v_fmamk_f32 v242, v242, 0x3a000000, v232
	v_fmamk_f32 v244, v244, 0x3a000000, v232
	v_fmamk_f32 v246, v246, 0x3a000000, v232
	v_fmamk_f32 v248, v248, 0x3a000000, v232
	v_fmamk_f32 v250, v250, 0x3a000000, v232
	v_rsq_f32_e32 v228, v228
	v_rsq_f32_e32 v230, v230
	v_rsq_f32_e32 v238, v238
	v_rsq_f32_e32 v242, v242
	v_rsq_f32_e32 v244, v244
	v_rsq_f32_e32 v246, v246
	v_rsq_f32_e32 v248, v248
	v_rsq_f32_e32 v250, v250
	s_nop 0

.LBB0_1060:
	s_sext_i32_i16 s4, s20
	s_add_u32 s20, s24, 0x2d300000
	s_addc_u32 s21, s25, 0
	v_bfe_u32 v21, v18, 4, 2
	s_lshl_b32 s6, s6, 5
	v_and_b32_e32 v19, 15, v18
	v_lshlrev_b32_e32 v20, 3, v21
	v_lshlrev_b32_e32 v21, 4, v21
	v_lshlrev_b32_e32 v18, 2, v18
	s_and_b32 s8, s6, 0x60
	s_add_i32 m0, s60, 0x18000
	v_lshl_add_u64 v[10:11], v[10:11], 0, s[68:69]
	v_lshl_or_b32 v161, s7, 6, v19
	v_lshl_or_b32 v19, v19, 6, v21
	s_lshl_b32 s7, s7, 13
	v_and_b32_e32 v18, 32, v18
	s_lshl_b32 s6, s8, 7
	s_nop 0
	global_load_lds_dwordx4 v[10:11], off
	v_lshl_add_u64 v[8:9], v[8:9], 0, s[68:69]
	s_add_i32 m0, s60, 0x1a000
	s_add_i32 s64, s60, 0x8000
	s_add_i32 s65, s60, 0xa000
	v_bitop3_b32 v163, v19, s6, v18 bitop3:0xde
	global_load_lds_dwordx4 v[8:9], off
	v_lshl_add_u64 v[4:5], v[4:5], 0, s[68:69]
	s_mov_b32 m0, s64
	s_add_u32 s6, s44, 0x80080
	v_bitop3_b32 v22, v19, s7, v18 bitop3:0xde
	global_load_lds_dwordx4 v[4:5], off
	v_lshl_add_u64 v[4:5], v[6:7], 0, s[68:69]
	s_mov_b32 m0, s65
	s_addc_u32 s7, s45, 0
	global_load_lds_dwordx4 v[4:5], off
	s_add_i32 m0, s60, 0x1c000
	v_lshl_add_u64 v[4:5], s[6:7], 0, v[2:3]
	global_load_lds_dwordx4 v[4:5], off
	v_lshl_add_u64 v[4:5], s[6:7], 0, v[0:1]
	s_add_i32 m0, s60, 0x1e000
	v_cmp_lt_i32_e32 vcc, v236, v237
	global_load_lds_dwordx4 v[4:5], off
	s_nop 0
	v_cndmask_b32_e32 v4, v234, v236, vcc
	v_cmp_lt_i32_e32 vcc, v252, v237
	v_lshlrev_b32_e32 v164, 2, v4
	v_mov_b32_e32 v21, v3
	v_cndmask_b32_e32 v4, v234, v252, vcc
	v_lshlrev_b32_e32 v165, 2, v4
	v_lshl_add_u64 v[4:5], s[24:25], 0, v[20:21]
	s_mov_b64 s[6:7], 0x800000
	v_lshl_add_u64 v[136:137], v[4:5], 0, s[6:7]
	v_lshl_add_u32 v168, s42, 8, v161
	v_or_b32_e32 v186, 16, v168
	v_or_b32_e32 v187, 32, v168
	v_or_b32_e32 v188, 48, v168
	v_add_u32_e32 v189, 0x80, v168
	v_add_u32_e32 v190, 0x90, v168
	v_add_u32_e32 v191, 0xa0, v168
	v_add_u32_e32 v192, 0xb0, v168
	v_mad_u64_u32 v[170:171], s[100:101], v168, 32, v[136:137]
	v_mad_u64_u32 v[172:173], s[100:101], v186, 32, v[136:137]
	v_mad_u64_u32 v[174:175], s[100:101], v187, 32, v[136:137]
	v_mad_u64_u32 v[176:177], s[100:101], v188, 32, v[136:137]
	v_mad_u64_u32 v[178:179], s[100:101], v189, 32, v[136:137]
	v_mad_u64_u32 v[180:181], s[100:101], v190, 32, v[136:137]
	v_mad_u64_u32 v[182:183], s[100:101], v191, 32, v[136:137]
	v_mad_u64_u32 v[184:185], s[100:101], v192, 32, v[136:137]
	global_load_dwordx2 v[228:229], v[170:171], off
	global_load_dwordx2 v[230:231], v[172:173], off
	global_load_dwordx2 v[238:239], v[174:175], off
	global_load_dwordx2 v[242:243], v[176:177], off
	global_load_dwordx2 v[244:245], v[178:179], off
	global_load_dwordx2 v[246:247], v[180:181], off
	global_load_dwordx2 v[248:249], v[182:183], off
	global_load_dwordx2 v[250:251], v[184:185], off
	v_lshlrev_b32_e32 v4, 15, v12
	v_and_b32_e32 v4, 0xffff0000, v4
	v_lshl_add_u32 v4, v13, 12, v4
	v_and_b32_e32 v5, 1, v12
	v_lshl_or_b32 v4, v5, 6, v4
	v_lshl_add_u32 v138, v14, 1, v4
	v_lshlrev_b32_e32 v4, 15, v16
	v_and_b32_e32 v4, 0xffff0000, v4
	s_waitcnt vmcnt(16)
	s_barrier
	s_waitcnt vmcnt(14)
	v_lshl_add_u32 v4, v15, 12, v4
	v_and_b32_e32 v5, 1, v16
	s_cmpk_lt_u32 s5, 0x100
	v_lshl_or_b32 v4, v5, 6, v4
	s_cselect_b64 s[22:23], -1, 0
	s_ashr_i32 s70, s50, 31
	v_or_b32_e32 v166, s8, v20
	v_mov_b32_e32 v139, v3
	v_lshl_add_u32 v140, v17, 1, v4
	v_mov_b32_e32 v141, v3
	s_mov_b32 s71, 0
	v_add_u32_e32 v167, 0, v22
	s_barrier
	s_branch .LBB0_1063

.LBB0_1069:
	v_lshl_add_u32 v142, s42, 8, v161
	v_or_b32_e32 v143, 16, v142
	v_or_b32_e32 v144, 32, v142
	v_or_b32_e32 v145, 48, v142
	v_add_u32_e32 v146, 0x80, v142
	v_add_u32_e32 v147, 0x90, v142
	v_add_u32_e32 v148, 0xa0, v142
	v_add_u32_e32 v149, 0xb0, v142
	s_cmp_eq_u32 s42, s98
	s_cbranch_scc1 .Lgu_scales_ready
	s_mov_b32 s98, s42
	s_waitcnt vmcnt(0)
	v_add_f32_e32 v228, v228, v229
	v_add_f32_e32 v230, v230, v231
	v_add_f32_e32 v238, v238, v239
	v_add_f32_e32 v242, v242, v243
	v_add_f32_e32 v244, v244, v245
	v_add_f32_e32 v246, v246, v247
	v_add_f32_e32 v248, v248, v249
	v_add_f32_e32 v250, v250, v251
	ds_bpermute_b32 v229, v164, v228
	ds_bpermute_b32 v231, v164, v230
	ds_bpermute_b32 v239, v164, v238
	ds_bpermute_b32 v243, v164, v242
	ds_bpermute_b32 v245, v164, v244
	ds_bpermute_b32 v247, v164, v246
	ds_bpermute_b32 v249, v164, v248
	ds_bpermute_b32 v251, v164, v250
	s_waitcnt lgkmcnt(0)
	v_add_f32_e32 v228, v228, v229
	v_add_f32_e32 v230, v230, v231
	v_add_f32_e32 v238, v238, v239
	v_add_f32_e32 v242, v242, v243
	v_add_f32_e32 v244, v244, v245
	v_add_f32_e32 v246, v246, v247
	v_add_f32_e32 v248, v248, v249
	v_add_f32_e32 v250, v250, v251
	ds_bpermute_b32 v229, v165, v228
	ds_bpermute_b32 v231, v165, v230
	ds_bpermute_b32 v239, v165, v238
	ds_bpermute_b32 v243, v165, v242
	ds_bpermute_b32 v245, v165, v244
	ds_bpermute_b32 v247, v165, v246
	ds_bpermute_b32 v249, v165, v248
	ds_bpermute_b32 v251, v165, v250
	s_waitcnt lgkmcnt(0)
	v_add_f32_e32 v228, v228, v229
	v_add_f32_e32 v230, v230, v231
	v_add_f32_e32 v238, v238, v239
	v_add_f32_e32 v242, v242, v243
	v_add_f32_e32 v244, v244, v245
	v_add_f32_e32 v246, v246, v247
	v_add_f32_e32 v248, v248, v249
	v_add_f32_e32 v250, v250, v251
	v_fmamk_f32 v228, v228, 0x3a000000, v232
	v_fmamk_f32 v230, v230, 0x3a000000, v232
	v_fmamk_f32 v238, v238, 0x3a000000, v232
	v_fmamk_f32 v242, v242, 0x3a000000, v232
	v_fmamk_f32 v244, v244, 0x3a000000, v232
	v_fmamk_f32 v246, v246, 0x3a000000, v232
	v_fmamk_f32 v248, v248, 0x3a000000, v232
	v_fmamk_f32 v250, v250, 0x3a000000, v232
	v_rsq_f32_e32 v228, v228
	v_rsq_f32_e32 v230, v230
	v_rsq_f32_e32 v238, v238
	v_rsq_f32_e32 v242, v242
	v_rsq_f32_e32 v244, v244
	v_rsq_f32_e32 v246, v246
	v_rsq_f32_e32 v248, v248
	v_rsq_f32_e32 v250, v250
	s_nop 0
